# APRIO: one static s_setprio 1 for waves 4-7 (the younger half) during the attention tile loop, back to 0 after it (on SO7)
# baseline (speedup 1.0000x reference)
.LBB0_987:
	s_waitcnt lgkmcnt(0)
	v_add_f32_e32 v2, v2, v3
	v_mul_f32_e32 v3, 0x4f800000, v2
	v_cmp_gt_f32_e32 vcc, s36, v2
	s_lshl_b32 s26, s42, 7
	s_add_i32 s42, s29, 0x2000
	v_cndmask_b32_e32 v2, v2, v3, vcc
	v_sqrt_f32_e32 v3, v2
	v_mov_b32_e32 v139, 0
	v_lshl_add_u32 v141, s41, 13, v154
	v_mov_b32_e32 v7, v139
	v_add_u32_e32 v5, -1, v3
	v_fma_f32 v6, -v5, v3, v2
	v_cmp_ge_f32_e64 s[4:5], 0, v6
	v_add_u32_e32 v6, 1, v3
	v_mov_b32_e32 v8, v139
	v_cndmask_b32_e64 v5, v3, v5, s[4:5]
	v_fma_f32 v3, -v6, v3, v2
	v_cmp_lt_f32_e64 s[4:5], 0, v3
	v_mov_b32_e32 v9, v139
	v_mov_b32_e32 v10, v139
	v_cndmask_b32_e64 v3, v5, v6, s[4:5]
	v_mul_f32_e32 v5, 0x37800000, v3
	v_cndmask_b32_e32 v3, v3, v5, vcc
	v_cmp_class_f32_e32 vcc, v2, v156
	s_add_i32 s4, s44, 1
	s_and_b32 s5, s45, 0x3ffffff0
	v_cndmask_b32_e32 v2, v3, v2, vcc
	v_mul_f32_e64 v66, v2, -v4
	v_lshl_add_u64 v[2:3], s[22:23], 0, v[134:135]
	s_add_u32 s22, s6, s5
	s_addc_u32 s23, 0, 0
	v_lshl_add_u64 v[144:145], v[2:3], 0, s[22:23]
	s_add_u32 s22, s6, s28
	s_addc_u32 s23, 0, 0
	s_lshl_b32 s5, s43, 9
	s_and_b32 s5, s5, 0x18000
	v_lshl_or_b32 v4, v155, 1, s5
	v_mov_b32_e32 v5, v131
	v_lshl_add_u64 v[2:3], s[24:25], 0, v[136:137]
	v_lshl_add_u64 v[4:5], s[22:23], 0, v[4:5]
	v_mov_b32_e32 v67, v66
	v_mov_b32_e32 v68, v66
	v_mov_b32_e32 v69, v66
	v_mov_b32_e32 v70, v66
	v_mov_b32_e32 v71, v66
	v_mov_b32_e32 v72, v66
	v_mov_b32_e32 v73, v66
	v_mov_b32_e32 v74, v66
	v_mov_b32_e32 v75, v66
	v_mov_b32_e32 v76, v66
	v_mov_b32_e32 v77, v66
	v_mov_b32_e32 v78, v66
	v_mov_b32_e32 v79, v66
	v_mov_b32_e32 v80, v66
	v_mov_b32_e32 v81, v66
	v_lshl_add_u64 v[146:147], v[2:3], 0, v[4:5]
	s_mov_b32 s6, 0
	v_mov_b32_e32 v2, 0
	v_mov_b32_e32 v3, v139
	v_mov_b32_e32 v4, v139
	v_mov_b32_e32 v5, v139
	v_mov_b32_e32 v6, v139
	v_mov_b32_e32 v11, v139
	v_mov_b32_e32 v12, v139
	v_mov_b32_e32 v13, v139
	v_mov_b32_e32 v14, v139
	v_mov_b32_e32 v15, v139
	v_mov_b32_e32 v16, v139
	v_mov_b32_e32 v17, v139
	v_mov_b32_e32 v18, 0
	v_mov_b32_e32 v19, v139
	v_mov_b32_e32 v20, v139
	v_mov_b32_e32 v21, v139
	v_mov_b32_e32 v22, v139
	v_mov_b32_e32 v23, v139
	v_mov_b32_e32 v24, v139
	v_mov_b32_e32 v25, v139
	v_mov_b32_e32 v26, v139
	v_mov_b32_e32 v27, v139
	v_mov_b32_e32 v28, v139
	v_mov_b32_e32 v29, v139
	v_mov_b32_e32 v30, v139
	v_mov_b32_e32 v31, v139
	v_mov_b32_e32 v32, v139
	v_mov_b32_e32 v33, v139
	v_mov_b32_e32 v34, 0
	v_mov_b32_e32 v35, v139
	v_mov_b32_e32 v36, v139
	v_mov_b32_e32 v37, v139
	v_mov_b32_e32 v38, v139
	v_mov_b32_e32 v39, v139
	v_mov_b32_e32 v40, v139
	v_mov_b32_e32 v41, v139
	v_mov_b32_e32 v42, v139
	v_mov_b32_e32 v43, v139
	v_mov_b32_e32 v44, v139
	v_mov_b32_e32 v45, v139
	v_mov_b32_e32 v46, v139
	v_mov_b32_e32 v47, v139
	v_mov_b32_e32 v48, v139
	v_mov_b32_e32 v49, v139
	v_mov_b32_e32 v50, 0
	v_mov_b32_e32 v51, v139
	v_mov_b32_e32 v52, v139
	v_mov_b32_e32 v53, v139
	v_mov_b32_e32 v54, v139
	v_mov_b32_e32 v55, v139
	v_mov_b32_e32 v56, v139
	v_mov_b32_e32 v57, v139
	v_mov_b32_e32 v58, v139
	v_mov_b32_e32 v59, v139
	v_mov_b32_e32 v60, v139
	v_mov_b32_e32 v61, v139
	v_mov_b32_e32 v62, v139
	v_mov_b32_e32 v63, v139
	v_mov_b32_e32 v64, v139
	v_mov_b32_e32 v65, v139
	s_cmp_gt_u32 s43, 255
	s_cbranch_scc0 .Lat3_prio
	s_setprio 1
.Lat3_prio:
	s_movk_i32 s23, 0x4000
	s_mov_b32 s28, m0
	s_add_i32 s24, s23, s29
	s_mov_b32 m0, s24
	s_add_i32 s25, s23, s42
	global_load_lds_dwordx4 v[144:145], off
	s_addk_i32 s25, 0xff80
	s_mov_b32 m0, s25
	s_add_i32 s24, s24, 0xc000
	global_load_lds_dwordx4 v[144:145], off offset:128
	s_mov_b32 m0, s24
	s_add_i32 s25, s25, 0xc000
	global_load_lds_dwordx4 v[146:147], off
	s_mov_b32 m0, s25
	v_lshl_add_u64 v[144:145], v[144:145], 0, s[18:19]
	global_load_lds_dwordx4 v[146:147], off offset:128
	s_mov_b32 m0, s28
	v_lshl_add_u64 v[146:147], v[146:147], 0, s[18:19]
	s_waitcnt vmcnt(4) lgkmcnt(0)
	s_barrier
	v_mov_b32_e32 v159, v141
	ds_read_b128 v[210:213], v159
	ds_read_b128 v[214:217], v159 offset:512
	ds_read_b128 v[218:221], v159 offset:2048
	ds_read_b128 v[222:225], v159 offset:2560
	ds_read_b128 v[226:229], v159 offset:4096
	ds_read_b128 v[230:233], v159 offset:4608
	ds_read_b128 v[234:237], v159 offset:6144
	ds_read_b128 v[238:241], v159 offset:6656
	s_waitcnt lgkmcnt(7)
	v_mfma_f32_32x32x16_bf16 v[98:113], v[210:213], v[126:129], v[66:81]
	s_waitcnt lgkmcnt(5)
	v_mfma_f32_32x32x16_bf16 v[98:113], v[218:221], v[122:125], v[98:113]
	s_waitcnt lgkmcnt(3)
	v_mfma_f32_32x32x16_bf16 v[98:113], v[226:229], v[118:121], v[98:113]
	s_waitcnt lgkmcnt(1)
	v_mfma_f32_32x32x16_bf16 v[98:113], v[234:237], v[114:117], v[98:113]
	v_mfma_f32_32x32x16_bf16 v[82:97], v[214:217], v[126:129], v[66:81]
	v_mfma_f32_32x32x16_bf16 v[82:97], v[222:225], v[122:125], v[82:97]
	v_mfma_f32_32x32x16_bf16 v[82:97], v[230:233], v[118:121], v[82:97]
	s_waitcnt lgkmcnt(0)
	v_mfma_f32_32x32x16_bf16 v[82:97], v[238:241], v[114:117], v[82:97]
	s_nop 6
	v_exp_f32_e32 v98, v98
	v_exp_f32_e32 v99, v99
	v_exp_f32_e32 v100, v100
	v_exp_f32_e32 v101, v101
	v_exp_f32_e32 v102, v102
	v_exp_f32_e32 v103, v103
	v_exp_f32_e32 v104, v104
	v_exp_f32_e32 v105, v105
	v_exp_f32_e32 v106, v106
	v_exp_f32_e32 v107, v107
	v_exp_f32_e32 v108, v108
	v_exp_f32_e32 v109, v109
	v_exp_f32_e32 v110, v110
	v_exp_f32_e32 v111, v111
	v_exp_f32_e32 v112, v112
	v_exp_f32_e32 v113, v113
	v_exp_f32_e32 v82, v82
	v_exp_f32_e32 v83, v83
	v_exp_f32_e32 v84, v84
	v_exp_f32_e32 v85, v85
	v_exp_f32_e32 v86, v86
	v_exp_f32_e32 v87, v87
	v_exp_f32_e32 v88, v88
	v_exp_f32_e32 v89, v89
	v_exp_f32_e32 v90, v90
	v_exp_f32_e32 v91, v91
	v_exp_f32_e32 v92, v92
	v_exp_f32_e32 v93, v93
	v_exp_f32_e32 v94, v94
	v_exp_f32_e32 v95, v95
	v_exp_f32_e32 v96, v96
	v_exp_f32_e32 v97, v97
	v_cvt_pk_bf16_f32 v194, v98, v99
	v_cvt_pk_bf16_f32 v195, v100, v101
	v_cvt_pk_bf16_f32 v196, v102, v103
	v_cvt_pk_bf16_f32 v197, v104, v105
	v_cvt_pk_bf16_f32 v198, v106, v107
	v_cvt_pk_bf16_f32 v199, v108, v109
	v_cvt_pk_bf16_f32 v200, v110, v111
	v_cvt_pk_bf16_f32 v201, v112, v113
	v_cvt_pk_bf16_f32 v202, v82, v83
	v_cvt_pk_bf16_f32 v203, v84, v85
	v_cvt_pk_bf16_f32 v204, v86, v87
	v_cvt_pk_bf16_f32 v205, v88, v89
	v_cvt_pk_bf16_f32 v206, v90, v91
	v_cvt_pk_bf16_f32 v207, v92, v93
	v_cvt_pk_bf16_f32 v208, v94, v95
	v_cvt_pk_bf16_f32 v209, v96, v97
	s_mov_b32 s6, 0

.Lat3_nodma:
	s_waitcnt lgkmcnt(8)
	v_mfma_f32_32x32x16_bf16 v[50:65], v[168:171], v[194:197], v[50:65]
	ds_read_b128 v[214:217], v159 offset:512
	ds_read_b128 v[222:225], v159 offset:2560
	v_add_f32_e32 v246, 0, v98
	v_add_f32_e32 v246, v99, v246
	v_add_f32_e32 v246, v100, v246
	v_add_f32_e32 v246, v101, v246
	v_add_f32_e32 v247, 0, v82
	v_add_f32_e32 v247, v83, v247
	v_mfma_f32_32x32x16_bf16 v[34:49], v[172:175], v[194:197], v[34:49]
	ds_read_b128 v[230:233], v159 offset:4608
	ds_read_b128 v[238:241], v159 offset:6656
	v_add_f32_e32 v246, v102, v246
	v_add_f32_e32 v246, v103, v246
	v_add_f32_e32 v246, v104, v246
	v_add_f32_e32 v246, v105, v246
	v_add_f32_e32 v247, v84, v247
	v_add_f32_e32 v247, v85, v247
	s_waitcnt lgkmcnt(8)
	v_mfma_f32_32x32x16_bf16 v[18:33], v[176:179], v[194:197], v[18:33]
	v_add_f32_e32 v246, v106, v246
	v_add_f32_e32 v246, v107, v246
	v_add_f32_e32 v246, v108, v246
	v_add_f32_e32 v246, v109, v246
	v_add_f32_e32 v247, v86, v247
	v_add_f32_e32 v247, v87, v247
	v_mfma_f32_32x32x16_bf16 v[2:17], v[180:183], v[194:197], v[2:17]
	v_add_f32_e32 v246, v110, v246
	v_add_f32_e32 v246, v111, v246
	v_add_f32_e32 v246, v112, v246
	v_add_f32_e32 v246, v113, v246
	v_add_f32_e32 v247, v88, v247
	v_add_f32_e32 v247, v89, v247
	v_add_f32_e32 v246, v139, v246
	ds_read_b64_tr_b16 v[184:185], v248 offset:50176
	ds_read_b64_tr_b16 v[186:187], v248 offset:50688
	ds_read_b64_tr_b16 v[188:189], v248 offset:54272
	ds_read_b64_tr_b16 v[190:191], v248 offset:54784
	s_waitcnt lgkmcnt(10)
	v_mfma_f32_32x32x16_bf16 v[98:113], v[210:213], v[126:129], v[66:81]
	v_add_f32_e32 v247, v90, v247
	v_add_f32_e32 v247, v91, v247
	v_mfma_f32_32x32x16_bf16 v[98:113], v[218:221], v[122:125], v[98:113]
	v_add_f32_e32 v247, v92, v247
	v_add_f32_e32 v247, v93, v247
	s_waitcnt lgkmcnt(8)
	v_mfma_f32_32x32x16_bf16 v[98:113], v[226:229], v[118:121], v[98:113]
	v_add_f32_e32 v247, v94, v247
	v_add_f32_e32 v247, v95, v247
	v_mfma_f32_32x32x16_bf16 v[98:113], v[234:237], v[114:117], v[98:113]
	v_add_f32_e32 v247, v96, v247
	v_add_f32_e32 v247, v97, v247
	v_add_f32_e32 v139, v246, v247
	ds_read_b64_tr_b16 v[160:161], v248 offset:58368
	ds_read_b64_tr_b16 v[162:163], v248 offset:58880
	ds_read_b64_tr_b16 v[242:243], v248 offset:62464
	ds_read_b64_tr_b16 v[244:245], v248 offset:62976
	s_waitcnt lgkmcnt(4)
	v_mfma_f32_32x32x16_bf16 v[50:65], v[184:187], v[198:201], v[50:65]
	v_mfma_f32_32x32x16_bf16 v[34:49], v[188:191], v[198:201], v[34:49]
	ds_read_b64_tr_b16 v[168:169], v248 offset:51200
	ds_read_b64_tr_b16 v[170:171], v248 offset:51712
	ds_read_b64_tr_b16 v[172:173], v248 offset:55296
	ds_read_b64_tr_b16 v[174:175], v248 offset:55808
	s_waitcnt lgkmcnt(4)
	v_mfma_f32_32x32x16_bf16 v[18:33], v[160:163], v[198:201], v[18:33]
	v_exp_f32_e32 v98, v98
	v_exp_f32_e32 v99, v99
	v_exp_f32_e32 v100, v100
	v_mfma_f32_32x32x16_bf16 v[2:17], v[242:245], v[198:201], v[2:17]
	ds_read_b64_tr_b16 v[176:177], v248 offset:59392
	ds_read_b64_tr_b16 v[178:179], v248 offset:59904
	ds_read_b64_tr_b16 v[180:181], v248 offset:63488
	ds_read_b64_tr_b16 v[182:183], v248 offset:64000
	v_exp_f32_e32 v101, v101
	v_exp_f32_e32 v102, v102
	v_mfma_f32_32x32x16_bf16 v[82:97], v[214:217], v[126:129], v[66:81]
	ds_read_b64_tr_b16 v[184:185], v248 offset:52224
	ds_read_b64_tr_b16 v[186:187], v248 offset:52736
	ds_read_b64_tr_b16 v[188:189], v248 offset:56320
	ds_read_b64_tr_b16 v[190:191], v248 offset:56832
	v_exp_f32_e32 v103, v103
	v_exp_f32_e32 v104, v104
	v_mfma_f32_32x32x16_bf16 v[82:97], v[222:225], v[122:125], v[82:97]
	v_exp_f32_e32 v105, v105
	v_exp_f32_e32 v106, v106
	v_exp_f32_e32 v107, v107
	v_mfma_f32_32x32x16_bf16 v[82:97], v[230:233], v[118:121], v[82:97]
	v_exp_f32_e32 v108, v108
	v_exp_f32_e32 v109, v109
	v_exp_f32_e32 v110, v110
	v_mfma_f32_32x32x16_bf16 v[82:97], v[238:241], v[114:117], v[82:97]
	v_exp_f32_e32 v111, v111
	v_exp_f32_e32 v112, v112
	v_exp_f32_e32 v113, v113
	s_waitcnt lgkmcnt(8)
	v_mfma_f32_32x32x16_bf16 v[50:65], v[168:171], v[202:205], v[50:65]
	v_cvt_pk_bf16_f32 v194, v98, v99
	v_cvt_pk_bf16_f32 v195, v100, v101
	v_cvt_pk_bf16_f32 v196, v102, v103
	v_cvt_pk_bf16_f32 v197, v104, v105
	v_mfma_f32_32x32x16_bf16 v[34:49], v[172:175], v[202:205], v[34:49]
	ds_read_b64_tr_b16 v[160:161], v248 offset:60416
	ds_read_b64_tr_b16 v[162:163], v248 offset:60928
	ds_read_b64_tr_b16 v[242:243], v248 offset:64512
	ds_read_b64_tr_b16 v[244:245], v248 offset:65024
	v_cvt_pk_bf16_f32 v198, v106, v107
	v_cvt_pk_bf16_f32 v199, v108, v109
	v_cvt_pk_bf16_f32 v200, v110, v111
	v_cvt_pk_bf16_f32 v201, v112, v113
	s_waitcnt lgkmcnt(8)
	v_mfma_f32_32x32x16_bf16 v[18:33], v[176:179], v[202:205], v[18:33]
	v_exp_f32_e32 v82, v82
	v_exp_f32_e32 v83, v83
	v_exp_f32_e32 v84, v84
	v_mfma_f32_32x32x16_bf16 v[2:17], v[180:183], v[202:205], v[2:17]
	v_exp_f32_e32 v85, v85
	v_exp_f32_e32 v86, v86
	v_exp_f32_e32 v87, v87
	s_waitcnt lgkmcnt(4)
	v_mfma_f32_32x32x16_bf16 v[50:65], v[184:187], v[206:209], v[50:65]
	v_exp_f32_e32 v88, v88
	v_exp_f32_e32 v89, v89
	v_exp_f32_e32 v90, v90
	v_mfma_f32_32x32x16_bf16 v[34:49], v[188:191], v[206:209], v[34:49]
	v_exp_f32_e32 v91, v91
	v_exp_f32_e32 v92, v92
	v_exp_f32_e32 v93, v93
	s_waitcnt lgkmcnt(0)
	v_mfma_f32_32x32x16_bf16 v[18:33], v[160:163], v[206:209], v[18:33]
	v_exp_f32_e32 v94, v94
	v_exp_f32_e32 v95, v95
	v_exp_f32_e32 v96, v96
	v_mfma_f32_32x32x16_bf16 v[2:17], v[242:245], v[206:209], v[2:17]
	v_exp_f32_e32 v97, v97
	v_cvt_pk_bf16_f32 v202, v82, v83
	v_cvt_pk_bf16_f32 v203, v84, v85
	v_cvt_pk_bf16_f32 v204, v86, v87
	v_cvt_pk_bf16_f32 v205, v88, v89
	v_cvt_pk_bf16_f32 v206, v90, v91
	v_cvt_pk_bf16_f32 v207, v92, v93
	v_cvt_pk_bf16_f32 v208, v94, v95
	v_cvt_pk_bf16_f32 v209, v96, v97
	s_add_i32 s4, s4, -1
	s_mov_b32 s6, s22
	s_cmp_eq_u32 s4, 0
	s_cbranch_scc0 .Lat3_loop
	s_setprio 0
	s_lshl_b32 s24, s6, 14
	v_add_u32_e32 v248, s24, v153
	ds_read_b64_tr_b16 v[168:169], v248 offset:49152
	ds_read_b64_tr_b16 v[170:171], v248 offset:49664
	ds_read_b64_tr_b16 v[172:173], v248 offset:53248
	ds_read_b64_tr_b16 v[174:175], v248 offset:53760
	ds_read_b64_tr_b16 v[176:177], v248 offset:57344
	ds_read_b64_tr_b16 v[178:179], v248 offset:57856
	ds_read_b64_tr_b16 v[180:181], v248 offset:61440
	ds_read_b64_tr_b16 v[182:183], v248 offset:61952
	s_waitcnt lgkmcnt(6)
	v_mfma_f32_32x32x16_bf16 v[50:65], v[168:171], v[194:197], v[50:65]
	v_add_f32_e32 v246, 0, v98
	v_add_f32_e32 v247, 0, v82
	v_add_f32_e32 v246, v99, v246
	v_add_f32_e32 v247, v83, v247
	s_waitcnt lgkmcnt(4)
	v_mfma_f32_32x32x16_bf16 v[34:49], v[172:175], v[194:197], v[34:49]
	ds_read_b64_tr_b16 v[184:185], v248 offset:50176
	ds_read_b64_tr_b16 v[186:187], v248 offset:50688
	ds_read_b64_tr_b16 v[188:189], v248 offset:54272
	ds_read_b64_tr_b16 v[190:191], v248 offset:54784
	v_add_f32_e32 v246, v100, v246
	v_add_f32_e32 v247, v84, v247
	v_add_f32_e32 v246, v101, v246
	v_add_f32_e32 v247, v85, v247
	s_waitcnt lgkmcnt(6)
	v_mfma_f32_32x32x16_bf16 v[18:33], v[176:179], v[194:197], v[18:33]
	v_add_f32_e32 v246, v102, v246
	v_add_f32_e32 v247, v86, v247
	v_add_f32_e32 v246, v103, v246
	v_add_f32_e32 v247, v87, v247
	s_waitcnt lgkmcnt(4)
	v_mfma_f32_32x32x16_bf16 v[2:17], v[180:183], v[194:197], v[2:17]
	ds_read_b64_tr_b16 v[160:161], v248 offset:58368
	ds_read_b64_tr_b16 v[162:163], v248 offset:58880
	ds_read_b64_tr_b16 v[242:243], v248 offset:62464
	ds_read_b64_tr_b16 v[244:245], v248 offset:62976
	v_add_f32_e32 v246, v104, v246
	v_add_f32_e32 v247, v88, v247
	v_add_f32_e32 v246, v105, v246
	v_add_f32_e32 v247, v89, v247
	s_waitcnt lgkmcnt(6)
	v_mfma_f32_32x32x16_bf16 v[50:65], v[184:187], v[198:201], v[50:65]
	v_add_f32_e32 v246, v106, v246
	v_add_f32_e32 v247, v90, v247
	v_add_f32_e32 v246, v107, v246
	v_add_f32_e32 v247, v91, v247
	s_waitcnt lgkmcnt(4)
	v_mfma_f32_32x32x16_bf16 v[34:49], v[188:191], v[198:201], v[34:49]
	ds_read_b64_tr_b16 v[168:169], v248 offset:51200
	ds_read_b64_tr_b16 v[170:171], v248 offset:51712
	ds_read_b64_tr_b16 v[172:173], v248 offset:55296
	ds_read_b64_tr_b16 v[174:175], v248 offset:55808
	v_add_f32_e32 v246, v108, v246
	v_add_f32_e32 v247, v92, v247
	v_add_f32_e32 v246, v109, v246
	v_add_f32_e32 v247, v93, v247
	s_waitcnt lgkmcnt(6)
	v_mfma_f32_32x32x16_bf16 v[18:33], v[160:163], v[198:201], v[18:33]
	v_add_f32_e32 v246, v110, v246
	v_add_f32_e32 v247, v94, v247
	v_add_f32_e32 v246, v111, v246
	v_add_f32_e32 v247, v95, v247
	s_waitcnt lgkmcnt(4)
	v_mfma_f32_32x32x16_bf16 v[2:17], v[242:245], v[198:201], v[2:17]
	ds_read_b64_tr_b16 v[176:177], v248 offset:59392
	ds_read_b64_tr_b16 v[178:179], v248 offset:59904
	ds_read_b64_tr_b16 v[180:181], v248 offset:63488
	ds_read_b64_tr_b16 v[182:183], v248 offset:64000
	v_add_f32_e32 v246, v112, v246
	v_add_f32_e32 v247, v96, v247
	v_add_f32_e32 v246, v113, v246
	v_add_f32_e32 v247, v97, v247
	v_add_f32_e32 v246, v139, v246
	v_add_f32_e32 v139, v246, v247
	v_mov_b32_e32 v90, v139
	ds_bpermute_b32 v91, v1, v90
	s_cmp_eq_u32 s41, 0
	s_cselect_b64 s[4:5], -1, 0
	s_waitcnt lgkmcnt(7)
	v_mfma_f32_32x32x16_bf16 v[50:65], v[168:171], v[202:205], v[50:65]
	s_waitcnt lgkmcnt(5)
	v_mfma_f32_32x32x16_bf16 v[34:49], v[172:175], v[202:205], v[34:49]
	ds_read_b64_tr_b16 v[184:185], v248 offset:52224
	ds_read_b64_tr_b16 v[186:187], v248 offset:52736
	ds_read_b64_tr_b16 v[188:189], v248 offset:56320
	ds_read_b64_tr_b16 v[190:191], v248 offset:56832
	s_waitcnt lgkmcnt(7)
	v_mfma_f32_32x32x16_bf16 v[18:33], v[176:179], v[202:205], v[18:33]
	s_waitcnt lgkmcnt(5)
	v_mfma_f32_32x32x16_bf16 v[2:17], v[180:183], v[202:205], v[2:17]
	ds_read_b64_tr_b16 v[160:161], v248 offset:60416
	ds_read_b64_tr_b16 v[162:163], v248 offset:60928
	ds_read_b64_tr_b16 v[242:243], v248 offset:64512
	ds_read_b64_tr_b16 v[244:245], v248 offset:65024
	s_waitcnt lgkmcnt(6)
	v_mfma_f32_32x32x16_bf16 v[50:65], v[184:187], v[206:209], v[50:65]
	s_waitcnt lgkmcnt(4)
	v_mfma_f32_32x32x16_bf16 v[34:49], v[188:191], v[206:209], v[34:49]
	s_waitcnt lgkmcnt(2)
	v_mfma_f32_32x32x16_bf16 v[18:33], v[160:163], v[206:209], v[18:33]
	s_waitcnt lgkmcnt(0)
	v_mfma_f32_32x32x16_bf16 v[2:17], v[242:245], v[206:209], v[2:17]
	v_add_f32_e32 v90, v90, v91
	v_cndmask_b32_e64 v91, v148, 1.0, s[4:5]
	v_div_scale_f32 v92, s[22:23], v90, v90, v91
	v_rcp_f32_e32 v93, v92
	s_waitcnt vmcnt(0) lgkmcnt(0)
	s_barrier
	v_fma_f32 v74, -v92, v93, 1.0
	v_fmac_f32_e32 v93, v74, v93
	v_div_scale_f32 v74, vcc, v91, v90, v91
	v_mul_f32_e32 v75, v74, v93
	v_fma_f32 v76, -v92, v75, v74
	v_fmac_f32_e32 v75, v76, v93
	v_fma_f32 v66, -v92, v75, v74
	s_nop 0
	v_div_fmas_f32 v66, v66, v93, v75
	v_div_fixup_f32 v82, v66, v90, v91
	v_lshl_add_u32 v70, s27, 13, v150
	s_and_b64 vcc, exec, s[4:5]
	s_cbranch_vccnz .LBB0_991
	v_mul_f32_e32 v66, v50, v82
	v_mul_f32_e32 v67, v51, v82
	v_cvt_pk_f16_f32 v66, v66, v67
	v_mul_f32_e32 v67, v52, v82
	v_mul_f32_e32 v68, v53, v82
	v_cvt_pk_f16_f32 v67, v67, v68
	ds_write2st64_b32 v70, v66, v67 offset1:1
	v_mul_f32_e32 v66, v54, v82
	v_mul_f32_e32 v67, v55, v82
	v_cvt_pk_f16_f32 v66, v66, v67
	v_mul_f32_e32 v67, v56, v82
	v_mul_f32_e32 v68, v57, v82
	v_cvt_pk_f16_f32 v67, v67, v68
	ds_write2st64_b32 v70, v66, v67 offset0:2 offset1:3
	v_mul_f32_e32 v66, v58, v82
	v_mul_f32_e32 v67, v59, v82
	v_cvt_pk_f16_f32 v66, v66, v67
	v_mul_f32_e32 v67, v60, v82
	v_mul_f32_e32 v68, v61, v82
	v_cvt_pk_f16_f32 v67, v67, v68
	ds_write2st64_b32 v70, v66, v67 offset0:4 offset1:5
	v_mul_f32_e32 v66, v62, v82
	v_mul_f32_e32 v67, v63, v82
	v_cvt_pk_f16_f32 v66, v66, v67
	v_mul_f32_e32 v67, v64, v82
	v_mul_f32_e32 v68, v65, v82
	v_cvt_pk_f16_f32 v67, v67, v68
	ds_write2st64_b32 v70, v66, v67 offset0:6 offset1:7
	v_mul_f32_e32 v66, v34, v82
	v_mul_f32_e32 v67, v35, v82
	v_cvt_pk_f16_f32 v66, v66, v67
	v_mul_f32_e32 v67, v36, v82
	v_mul_f32_e32 v68, v37, v82
	v_cvt_pk_f16_f32 v67, v67, v68
	ds_write2st64_b32 v70, v66, v67 offset0:8 offset1:9
	v_mul_f32_e32 v66, v38, v82
	v_mul_f32_e32 v67, v39, v82
	v_cvt_pk_f16_f32 v66, v66, v67
	v_mul_f32_e32 v67, v40, v82
	v_mul_f32_e32 v68, v41, v82
	v_cvt_pk_f16_f32 v67, v67, v68
	ds_write2st64_b32 v70, v66, v67 offset0:10 offset1:11
	v_mul_f32_e32 v66, v42, v82
	v_mul_f32_e32 v67, v43, v82
	v_cvt_pk_f16_f32 v66, v66, v67
	v_mul_f32_e32 v67, v44, v82
	v_mul_f32_e32 v68, v45, v82
	v_cvt_pk_f16_f32 v67, v67, v68
	ds_write2st64_b32 v70, v66, v67 offset0:12 offset1:13
	v_mul_f32_e32 v66, v46, v82
	v_mul_f32_e32 v67, v47, v82
	v_cvt_pk_f16_f32 v66, v66, v67
	v_mul_f32_e32 v67, v48, v82
	v_mul_f32_e32 v68, v49, v82
	v_cvt_pk_f16_f32 v67, v67, v68
	ds_write2st64_b32 v70, v66, v67 offset0:14 offset1:15
	v_mul_f32_e32 v66, v18, v82
	v_mul_f32_e32 v67, v19, v82
	v_cvt_pk_f16_f32 v66, v66, v67
	v_mul_f32_e32 v67, v20, v82
	v_mul_f32_e32 v68, v21, v82
	v_cvt_pk_f16_f32 v67, v67, v68
	ds_write2st64_b32 v70, v66, v67 offset0:16 offset1:17
	v_mul_f32_e32 v66, v22, v82
	v_mul_f32_e32 v67, v23, v82
	v_cvt_pk_f16_f32 v66, v66, v67
	v_mul_f32_e32 v67, v24, v82
	v_mul_f32_e32 v68, v25, v82
	v_cvt_pk_f16_f32 v67, v67, v68
	ds_write2st64_b32 v70, v66, v67 offset0:18 offset1:19
	v_mul_f32_e32 v66, v26, v82
	v_mul_f32_e32 v67, v27, v82
	v_cvt_pk_f16_f32 v66, v66, v67
	v_mul_f32_e32 v67, v28, v82
	v_mul_f32_e32 v68, v29, v82
	v_cvt_pk_f16_f32 v67, v67, v68
	ds_write2st64_b32 v70, v66, v67 offset0:20 offset1:21
	v_mul_f32_e32 v66, v30, v82
	v_mul_f32_e32 v67, v31, v82
	v_cvt_pk_f16_f32 v66, v66, v67
	v_mul_f32_e32 v67, v32, v82
	v_mul_f32_e32 v68, v33, v82
	v_cvt_pk_f16_f32 v67, v67, v68
	ds_write2st64_b32 v70, v66, v67 offset0:22 offset1:23
	v_mul_f32_e32 v66, v2, v82
	v_mul_f32_e32 v67, v3, v82
	v_cvt_pk_f16_f32 v66, v66, v67
	v_mul_f32_e32 v67, v4, v82
	v_mul_f32_e32 v68, v5, v82
	v_cvt_pk_f16_f32 v67, v67, v68
	ds_write2st64_b32 v70, v66, v67 offset0:24 offset1:25
	v_mul_f32_e32 v66, v6, v82
	v_mul_f32_e32 v67, v7, v82
	v_cvt_pk_f16_f32 v66, v66, v67
	v_mul_f32_e32 v67, v8, v82
	v_mul_f32_e32 v68, v9, v82
	v_cvt_pk_f16_f32 v67, v67, v68
	ds_write2st64_b32 v70, v66, v67 offset0:26 offset1:27
	v_mul_f32_e32 v66, v10, v82
	v_mul_f32_e32 v67, v11, v82
	v_cvt_pk_f16_f32 v66, v66, v67
	v_mul_f32_e32 v67, v12, v82
	v_mul_f32_e32 v68, v13, v82
	v_cvt_pk_f16_f32 v67, v67, v68
	ds_write2st64_b32 v70, v66, v67 offset0:28 offset1:29
	v_mul_f32_e32 v66, v14, v82
	v_mul_f32_e32 v67, v15, v82
	v_cvt_pk_f16_f32 v66, v66, v67
	v_mul_f32_e32 v67, v16, v82
	v_mul_f32_e32 v68, v17, v82
	v_cvt_pk_f16_f32 v67, v67, v68
	ds_write2st64_b32 v70, v66, v67 offset0:30 offset1:31
